# next-unit prefetch: the 8 A-fragment ds_reads of the next unit's first K-tile are issued inside the int8 epilogue (and after the phase prologue) instead of in the first load segment
# baseline (speedup 1.0000x reference)
.LBB0_286:
	s_lshl_b32 s15, s12, 12
	s_add_i32 m0, s63, 0x18000
	v_lshl_add_u64 v[8:9], v[8:9], 0, s[18:19]
	s_and_b32 s15, s15, 0x3000
	s_waitcnt vmcnt(2)
	s_barrier
	global_load_lds_dwordx4 v[8:9], off
	v_lshl_add_u64 v[6:7], v[6:7], 0, s[18:19]
	s_add_i32 m0, s63, 0x1a000
	s_add_i32 s71, s63, 0x8000
	s_add_i32 s72, s63, 0xa000
	global_load_lds_dwordx4 v[6:7], off
	v_lshl_add_u64 v[2:3], v[2:3], 0, s[18:19]
	s_mov_b32 m0, s71
	s_add_u32 s16, s34, 0x40080
	global_load_lds_dwordx4 v[2:3], off
	v_lshl_add_u64 v[2:3], v[4:5], 0, s[18:19]
	s_mov_b32 m0, s72
	s_addc_u32 s17, s35, 0
	global_load_lds_dwordx4 v[2:3], off
	s_add_i32 m0, s63, 0x1c000
	v_lshl_add_u64 v[2:3], s[16:17], 0, v[34:35]
	global_load_lds_dwordx4 v[2:3], off
	v_lshl_add_u64 v[2:3], s[16:17], 0, v[210:211]
	s_add_i32 m0, s63, 0x1e000
	s_cmp_lt_i32 s12, 2
	global_load_lds_dwordx4 v[2:3], off
	v_lshl_or_b32 v2, s13, 13, v242
	s_cselect_b64 s[12:13], -1, 0
	s_cmp_lt_u32 s14, 64
	v_lshlrev_b32_e32 v3, 2, v241
	v_and_b32_e32 v4, 0x7c, v3
	s_cselect_b64 s[38:39], -1, 0
	v_cndmask_b32_e64 v214, v4, v3, s[38:39]
	v_lshlrev_b32_e32 v3, 14, v10
	v_and_b32_e32 v3, 0xffff8000, v3
	v_lshl_add_u32 v3, v11, 11, v3
	v_and_b32_e32 v4, 1, v10
	v_lshl_or_b32 v3, v4, 6, v3
	v_lshl_add_u32 v218, v12, 1, v3
	v_lshlrev_b32_e32 v3, 14, v13
	v_and_b32_e32 v3, 0xffff8000, v3
	s_waitcnt vmcnt(6)
	v_mov_b32_e32 v5, s61
	v_mov_b32_e32 v6, s45
	v_cmp_gt_u32_e32 vcc, 32, v241
	v_lshl_add_u32 v3, v14, 11, v3
	v_and_b32_e32 v4, 1, v13
	s_cmpk_lt_u32 s14, 0x100
	v_cndmask_b32_e32 v213, v5, v6, vcc
	v_mov_b32_e32 v5, s60
	v_mov_b32_e32 v6, s44
	v_lshl_or_b32 v3, v4, 6, v3
	v_or_b32_e32 v243, s15, v242
	s_cselect_b64 s[14:15], -1, 0
	v_cndmask_b32_e32 v212, v5, v6, vcc
	v_mov_b32_e32 v215, v35
	v_mov_b32_e32 v216, v196
	v_mov_b32_e32 v217, v196
	v_mov_b32_e32 v219, v35
	v_lshl_add_u32 v220, v15, 1, v3
	v_mov_b32_e32 v221, v35
	s_mov_b32 s73, 0
	v_add_u32_e32 v244, 0, v2
	s_barrier
	ds_read_b128 v[188:191], v244
	ds_read_b128 v[192:195], v244 offset:1024
	ds_read_b128 v[180:183], v244 offset:2048
	ds_read_b128 v[184:187], v244 offset:3072
	ds_read_b128 v[172:175], v244 offset:4096
	ds_read_b128 v[176:179], v244 offset:5120
	ds_read_b128 v[164:167], v244 offset:6144
	ds_read_b128 v[168:171], v244 offset:7168
	s_branch .LBB0_289

.LP8_293:
	v_add_u32_e32 v132, 0, v243
	v_add_u32_e32 v133, 0x10000, v132
	v_add_u32_e32 v144, 0x14000, v132
	ds_read_b128 v[148:151], v133
	ds_read_b128 v[152:155], v133 offset:1024
	ds_read_b128 v[156:159], v133 offset:2048
	ds_read_b128 v[160:163], v133 offset:3072
	ds_read_b128 v[132:135], v144
	ds_read_b128 v[136:139], v144 offset:1024
	ds_read_b128 v[140:143], v144 offset:2048
	ds_read_b128 v[144:147], v144 offset:3072
	v_lshl_add_u64 v[246:247], v[224:225], 0, s[34:35]
	s_add_i32 m0, s63, 0xc000
	global_load_lds_dwordx4 v[246:247], off
	v_lshl_add_u64 v[246:247], v[226:227], 0, s[34:35]
	s_add_i32 m0, s63, 0xe000
	s_cmp_eq_u32 s34, 0
	global_load_lds_dwordx4 v[246:247], off
	s_waitcnt vmcnt(8)
	s_waitcnt lgkmcnt(0)
	s_cselect_b64 s[36:37], -1, 0
	s_and_b64 s[36:37], s[36:37], s[12:13]
	s_andn2_b64 vcc, exec, s[36:37]
	s_add_u32 s36, s28, s34
	s_addc_u32 s37, s29, s35
	s_add_u32 s36, s36, 0x100
	s_addc_u32 s37, s37, 0
	s_add_u32 s77, s27, s34
	s_addc_u32 s78, s31, s35
	s_cmpk_eq_i32 s34, 0x700
	s_cselect_b32 s43, s21, s37
	s_cselect_b32 s42, s74, s36
	s_cselect_b32 s37, s17, s78
	s_cselect_b32 s36, s75, s77
	s_setprio 1
	s_barrier
	s_cbranch_vccz .LP8_rss

.LBB0_305:
	ds_read_b128 v[188:191], v244
	ds_read_b128 v[192:195], v244 offset:1024
	ds_read_b128 v[180:183], v244 offset:2048
	ds_read_b128 v[184:187], v244 offset:3072
	ds_read_b128 v[172:175], v244 offset:4096
	ds_read_b128 v[176:179], v244 offset:5120
	ds_read_b128 v[164:167], v244 offset:6144
	ds_read_b128 v[168:171], v244 offset:7168
	v_pk_mul_f32 v[100:101], v[150:151], v[154:155] op_sel_hi:[1,0]
	v_cvt_f32_i32_e32 v95, v95
	v_pk_mul_f32 v[100:101], v[100:101], v[96:97]
	v_pk_mul_f32 v[92:93], v[96:97], v[92:93]
	v_cvt_f32_i32_e32 v97, v99
	v_cvt_f32_i32_e32 v96, v98
	v_mul_f32_e32 v102, v154, v154
	v_pk_mul_f32 v[98:99], v[146:147], v[102:103] op_sel_hi:[1,0]
	v_cvt_f32_i32_e32 v85, v85
	v_pk_mul_f32 v[92:93], v[92:93], v[98:99]
	v_pk_mul_f32 v[98:99], v[144:145], v[154:155] op_sel_hi:[1,0]
	v_pk_mul_f32 v[94:95], v[96:97], v[94:95]
	v_pk_mul_f32 v[98:99], v[98:99], v[96:97]
	v_cvt_f32_i32_e32 v97, v89
	v_cvt_f32_i32_e32 v96, v88
	v_pk_mul_f32 v[88:89], v[142:143], v[102:103] op_sel_hi:[1,0]
	v_cvt_f32_i32_e32 v84, v84
	v_pk_mul_f32 v[88:89], v[94:95], v[88:89]
	v_pk_mul_f32 v[94:95], v[140:141], v[154:155] op_sel_hi:[1,0]
	v_cvt_f32_i32_e32 v91, v91
	v_pk_mul_f32 v[94:95], v[94:95], v[96:97]
	v_cvt_f32_i32_e32 v90, v90
	v_exp_f32_e32 v94, v94
	v_exp_f32_e32 v95, v95
	v_pk_mul_f32 v[84:85], v[96:97], v[84:85]
	v_pk_mul_f32 v[96:97], v[138:139], v[102:103] op_sel_hi:[1,0]
	v_exp_f32_e32 v100, v100
	v_pk_mul_f32 v[84:85], v[84:85], v[96:97]
	v_pk_mul_f32 v[96:97], v[136:137], v[154:155] op_sel_hi:[1,0]
	v_pk_add_f32 v[94:95], v[94:95], 1.0 op_sel_hi:[1,0]
	v_pk_mul_f32 v[96:97], v[96:97], v[90:91]
	v_exp_f32_e32 v101, v101
	v_exp_f32_e32 v98, v98
	v_exp_f32_e32 v99, v99
	v_rcp_f32_e32 v94, v94
	v_rcp_f32_e32 v95, v95
	v_exp_f32_e32 v96, v96
	v_exp_f32_e32 v97, v97
	v_pk_add_f32 v[100:101], v[100:101], 1.0 op_sel_hi:[1,0]
	v_pk_add_f32 v[98:99], v[98:99], 1.0 op_sel_hi:[1,0]
	v_pk_mul_f32 v[84:85], v[84:85], v[94:95]
	v_pk_add_f32 v[94:95], v[96:97], 1.0 op_sel_hi:[1,0]
	v_rcp_f32_e32 v100, v100
	v_rcp_f32_e32 v101, v101
	v_rcp_f32_e32 v98, v98
	v_rcp_f32_e32 v99, v99
	v_rcp_f32_e32 v94, v94
	v_rcp_f32_e32 v95, v95
	v_pk_mul_f32 v[86:87], v[90:91], v[86:87]
	v_pk_mul_f32 v[90:91], v[134:135], v[102:103] op_sel_hi:[1,0]
	v_pk_mul_f32 v[92:93], v[92:93], v[100:101]
	v_pk_mul_f32 v[86:87], v[86:87], v[90:91]
	v_pk_mul_f32 v[88:89], v[88:89], v[98:99]
	v_pk_mul_f32 v[86:87], v[86:87], v[94:95]
	v_or_b32_e32 v90, 32, v128
	s_and_b64 vcc, exec, s[42:43]
	s_mov_b64 s[26:27], -1
	s_cbranch_vccnz .LBB0_307
	v_cvt_pk_fp8_f32 v94, v92, v93
	v_cvt_pk_fp8_f32 v95, v84, v85
	v_mad_u32_u24 v96, v90, s92, v132
	v_cvt_pk_fp8_f32 v94, v88, v89 op_sel:[0,0,1]
	v_cvt_pk_fp8_f32 v95, v86, v87 op_sel:[0,0,1]
	s_mov_b64 s[26:27], 0
	global_store_dwordx2 v96, v[94:95], s[8:9]

.LBB0_332:
	s_waitcnt lgkmcnt(0)
	s_waitcnt vmcnt(0)
	v_readlane_b32 s64, v255, 1
	v_readlane_b32 s70, v252, 4
	v_readlane_b32 s65, v255, 2
	v_readlane_b32 s71, v252, 5
	s_barrier
